# P1 row loop: loop-invariant norm-weight loads hoisted out of the loop (4 of 16 loads per row)
# baseline (speedup 1.0000x reference)
.LBB0_207:
	s_or_b64 exec, exec, s[0:1]
	v_readlane_b32 s0, v247, 2
	v_readlane_b32 s1, v247, 3
	v_readlane_b32 s0, v247, 0
	v_readlane_b32 s6, v247, 8
	s_lshl_b32 s18, s0, 2
	s_lshl_b32 s30, s6, 2
	v_add_u32_e32 v132, s18, v129
	s_mov_b32 s19, 0x8000
	v_add_u32_e32 v138, s30, v132
	v_readlane_b32 s1, v247, 1
	v_cmp_gt_i32_e64 s[34:35], s19, v132
	v_ashrrev_i32_e32 v133, 31, v132
	v_mbcnt_lo_u32_b32 v192, -1, 0
	v_ashrrev_i32_e32 v139, 31, v138
	s_waitcnt lgkmcnt(0)
	s_barrier
	v_readlane_b32 s2, v247, 4
	v_readlane_b32 s3, v247, 5
	v_readlane_b32 s4, v247, 6
	v_readlane_b32 s5, v247, 7
	v_readlane_b32 s7, v247, 9
	s_and_saveexec_b64 s[0:1], s[34:35]
	s_cbranch_execz .LBB0_214
	v_readlane_b32 s36, v247, 13
	v_readlane_b32 s37, v247, 14
	v_lshlrev_b64 v[0:1], 12, v[132:133]
	s_mov_b64 s[12:13], s[36:37]
	v_lshl_add_u64 v[0:1], s[12:13], 0, v[0:1]
	v_lshlrev_b32_e32 v40, 4, v128
	v_mov_b32_e32 v41, 0
	v_lshl_add_u64 v[0:1], v[0:1], 0, v[40:41]
	global_load_dwordx4 v[24:27], v[0:1], off
	global_load_dwordx4 v[20:23], v[0:1], off offset:1024
	global_load_dwordx4 v[28:31], v[0:1], off offset:2048
	s_nop 0
	global_load_dwordx4 v[0:3], v[0:1], off offset:3072
	v_mbcnt_hi_u32_b32 v4, -1, v192
	v_and_b32_e32 v6, 64, v4
	v_xor_b32_e32 v5, 16, v4
	v_add_u32_e32 v6, 64, v6
	v_cmp_lt_i32_e32 vcc, v5, v6
	v_lshlrev_b64 v[12:13], 10, v[132:133]
	v_readlane_b32 s44, v247, 21
	v_cndmask_b32_e32 v5, v4, v5, vcc
	v_lshlrev_b32_e32 v62, 2, v5
	v_xor_b32_e32 v5, 32, v4
	v_cmp_lt_i32_e32 vcc, v5, v6
	v_readlane_b32 s45, v247, 22
	v_readlane_b32 s46, v247, 23
	v_cndmask_b32_e32 v4, v4, v5, vcc
	v_lshlrev_b32_e32 v63, 2, v4
	v_lshlrev_b32_e32 v4, 2, v128
	v_or_b32_e32 v12, v12, v4
	v_lshl_add_u64 v[46:47], s[64:65], 0, v[12:13]
	v_lshlrev_b64 v[12:13], 12, v[138:139]
	v_readlane_b32 s47, v247, 24
	v_readlane_b32 s48, v247, 25
	v_readlane_b32 s49, v247, 26
	v_readlane_b32 s50, v247, 27
	v_readlane_b32 s51, v247, 28
	s_mov_b64 s[20:21], s[44:45]
	v_or_b32_e32 v6, 0x100, v4
	v_or_b32_e32 v8, 0x200, v4
	v_or_b32_e32 v10, 0x300, v4
	s_ashr_i32 s31, s30, 31
	v_or_b32_e32 v12, v12, v40
	v_cmp_eq_u32_e64 s[6:7], 0, v128
	v_lshl_add_u64 v[42:43], s[20:21], 0, v[40:41]
	v_lshl_add_u64 v[44:45], v[132:133], 2, s[54:55]
	s_lshl_b64 s[2:3], s[30:31], 2
	s_lshl_b64 s[4:5], s[30:31], 10
	v_lshl_add_u64 v[48:49], s[12:13], 0, v[12:13]
	s_lshl_b64 s[12:13], s[30:31], 12
	s_mov_b64 s[14:15], 0
	v_mov_b32_e32 v64, 0x358637bd
	v_lshlrev_b32_e32 v40, 2, v4
	v_lshlrev_b32_e32 v50, 2, v6
	v_mov_b32_e32 v51, v41
	v_lshlrev_b32_e32 v52, 2, v8
	v_mov_b32_e32 v53, v41
	v_lshlrev_b32_e32 v54, 2, v10
	v_mov_b32_e32 v55, v41
	s_mov_b32 s20, 0x43600000
	v_mov_b32_e32 v32, v132
	v_readlane_b32 s38, v247, 15
	v_readlane_b32 s39, v247, 16
	v_readlane_b32 s40, v247, 17
	v_readlane_b32 s41, v247, 18
	v_readlane_b32 s42, v247, 19
	v_readlane_b32 s43, v247, 20
	s_mov_b64 s[22:23], s[46:47]
	s_mov_b64 s[24:25], s[48:49]
	s_mov_b64 s[26:27], s[50:51]
	s_waitcnt vmcnt(3)
	v_mov_b32_e32 v35, v27
	s_waitcnt vmcnt(2)
	v_mov_b32_e32 v34, v23
	s_waitcnt vmcnt(1)
	v_mov_b32_e32 v57, v31
	s_waitcnt vmcnt(0)
	v_mov_b32_e32 v56, v3
	v_mov_b32_e32 v3, v30
	v_mov_b32_e32 v58, v1
	v_mov_b32_e32 v59, v29
	v_mov_b32_e32 v1, v28
	v_mov_b32_e32 v23, v26
	v_mov_b32_e32 v36, v21
	v_mov_b32_e32 v37, v25
	v_mov_b32_e32 v21, v24
	global_load_dwordx4 v[76:79], v[42:43], off
	global_load_dwordx4 v[80:83], v[42:43], off offset:1024
	global_load_dwordx4 v[84:87], v[42:43], off offset:2048
	global_load_dwordx4 v[88:91], v[42:43], off offset:3072
	s_branch .LBB0_210

.LBB0_210:
	v_add_u32_e32 v65, s30, v32
	s_movk_i32 s8, 0x7fff
	v_cmp_gt_i32_e32 vcc, s19, v65
	v_cmp_lt_i32_e64 s[8:9], s8, v65
	v_ashrrev_i32_e32 v24, 11, v32
	v_mul_i32_i24_e32 v24, 0x1800, v24
	s_mov_b64 s[10:11], 0x1000
	v_ashrrev_i32_e32 v25, 31, v24
	v_lshl_add_u64 v[24:25], v[24:25], 2, s[86:87]
	v_lshl_add_u64 v[32:33], v[24:25], 0, s[10:11]
	v_lshl_add_u64 v[60:61], v[24:25], 0, v[40:41]
	v_lshl_add_u64 v[26:27], v[32:33], 0, v[40:41]
	v_lshl_add_u64 v[28:29], v[32:33], 0, v[50:51]
	v_lshl_add_u64 v[30:31], v[32:33], 0, v[52:53]
	v_lshl_add_u64 v[32:33], v[32:33], 0, v[54:55]
	global_load_dwordx4 v[92:95], v[26:27], off
	global_load_dwordx4 v[96:99], v[28:29], off
	global_load_dwordx4 v[100:103], v[30:31], off
	global_load_dwordx4 v[104:107], v[32:33], off
	global_load_dwordx4 v[108:111], v[60:61], off
	global_load_dwordx4 v[112:115], v[60:61], off offset:1024
	global_load_dwordx4 v[116:119], v[60:61], off offset:2048
	global_load_dwordx4 v[120:123], v[60:61], off offset:3072
	s_sub_u32 s24, 0, s12
	s_subb_u32 s25, 0, s13
	v_lshl_add_u64 v[124:125], v[48:49], 0, s[24:25]
	v_cndmask_b32_e32 v126, v124, v48, vcc
	v_cndmask_b32_e32 v127, v125, v49, vcc
	global_load_dwordx4 v[4:7], v[126:127], off
	global_load_dwordx4 v[8:11], v[126:127], off offset:1024
	global_load_dwordx4 v[12:15], v[126:127], off offset:2048
	global_load_dwordx4 v[16:19], v[126:127], off offset:3072
	v_pk_mul_f32 v[24:25], v[20:21], v[20:21]
	v_pk_mul_f32 v[26:27], v[0:1], v[0:1]
	v_pk_fma_f32 v[24:25], v[36:37], v[36:37], v[24:25]
	v_pk_fma_f32 v[26:27], v[58:59], v[58:59], v[26:27]
	v_pk_fma_f32 v[24:25], v[22:23], v[22:23], v[24:25]
	v_pk_fma_f32 v[26:27], v[2:3], v[2:3], v[26:27]
	v_pk_fma_f32 v[24:25], v[34:35], v[34:35], v[24:25]
	v_pk_fma_f32 v[26:27], v[56:57], v[56:57], v[26:27]
	v_add_f32_e32 v24, v24, v25
	v_add_f32_e32 v24, v27, v24
	v_add_f32_e32 v24, v26, v24
	s_mov_b32 s10, 0x800000
	v_add_f32_dpp v24, v24, v24 row_ror:8 row_mask:0xf bank_mask:0xf bound_ctrl:1
	s_nop 1
	v_add_f32_dpp v24, v24, v24 row_ror:4 row_mask:0xf bank_mask:0xf bound_ctrl:1
	s_nop 1
	v_add_f32_dpp v24, v24, v24 row_ror:2 row_mask:0xf bank_mask:0xf bound_ctrl:1
	s_nop 1
	v_add_f32_dpp v24, v24, v24 row_ror:1 row_mask:0xf bank_mask:0xf bound_ctrl:1
	s_nop 1
	v_mov_b32_e32 v25, v24
	s_nop 1
	v_permlane16_swap_b32_e32 v25, v24
	s_nop 1
	v_add_f32_e32 v24, v24, v25
	s_nop 1
	v_mov_b32_e32 v25, v24
	s_nop 1
	v_permlane32_swap_b32_e32 v25, v24
	s_nop 1
	v_add_f32_e32 v24, v24, v25
	v_fmamk_f32 v24, v24, 0x3a800000, v64
	v_cmp_gt_f32_e32 vcc, s10, v24
	v_mul_f32_e32 v25, 0x4b800000, v24
	v_cndmask_b32_e32 v24, v24, v25, vcc
	v_rsq_f32_e32 v24, v24
	s_nop 0
	v_mul_f32_e32 v25, 0x45800000, v24
	v_cndmask_b32_e32 v66, v24, v25, vcc
	s_waitcnt vmcnt(4)
	v_mul_f32_e32 v142, v21, v66
	v_add_f32_e32 v143, 1.0, v92
	v_mul_f32_e32 v142, v76, v142
	v_fma_f32 v24, v143, v142, v108
	v_mul_f32_e32 v142, v37, v66
	v_add_f32_e32 v143, 1.0, v93
	v_mul_f32_e32 v142, v77, v142
	v_fma_f32 v25, v143, v142, v109
	v_mul_f32_e32 v142, v23, v66
	v_add_f32_e32 v143, 1.0, v94
	v_mul_f32_e32 v142, v78, v142
	v_fma_f32 v26, v143, v142, v110
	v_mul_f32_e32 v142, v35, v66
	v_add_f32_e32 v143, 1.0, v95
	v_mul_f32_e32 v142, v79, v142
	v_fma_f32 v27, v143, v142, v111
	v_mul_f32_e32 v142, v20, v66
	v_add_f32_e32 v143, 1.0, v96
	v_mul_f32_e32 v142, v80, v142
	v_fma_f32 v28, v143, v142, v112
	v_mul_f32_e32 v142, v36, v66
	v_add_f32_e32 v143, 1.0, v97
	v_mul_f32_e32 v142, v81, v142
	v_fma_f32 v67, v143, v142, v113
	v_mul_f32_e32 v142, v22, v66
	v_add_f32_e32 v143, 1.0, v98
	v_mul_f32_e32 v142, v82, v142
	v_fma_f32 v29, v143, v142, v114
	v_mul_f32_e32 v142, v34, v66
	v_add_f32_e32 v143, 1.0, v99
	v_mul_f32_e32 v142, v83, v142
	v_fma_f32 v31, v143, v142, v115
	v_mul_f32_e32 v142, v1, v66
	v_add_f32_e32 v143, 1.0, v100
	v_mul_f32_e32 v142, v84, v142
	v_fma_f32 v1, v143, v142, v116
	v_mul_f32_e32 v142, v59, v66
	v_add_f32_e32 v143, 1.0, v101
	v_mul_f32_e32 v142, v85, v142
	v_fma_f32 v59, v143, v142, v117
	v_mul_f32_e32 v142, v3, v66
	v_add_f32_e32 v143, 1.0, v102
	v_mul_f32_e32 v142, v86, v142
	v_fma_f32 v3, v143, v142, v118
	v_mul_f32_e32 v142, v57, v66
	v_add_f32_e32 v143, 1.0, v103
	v_mul_f32_e32 v142, v87, v142
	v_fma_f32 v23, v143, v142, v119
	v_mul_f32_e32 v142, v0, v66
	v_add_f32_e32 v143, 1.0, v104
	v_mul_f32_e32 v142, v88, v142
	v_fma_f32 v20, v143, v142, v120
	v_mul_f32_e32 v142, v58, v66
	v_add_f32_e32 v143, 1.0, v105
	v_mul_f32_e32 v142, v89, v142
	v_fma_f32 v21, v143, v142, v121
	v_mul_f32_e32 v142, v2, v66
	v_add_f32_e32 v143, 1.0, v106
	v_mul_f32_e32 v142, v90, v142
	v_fma_f32 v2, v143, v142, v122
	v_mul_f32_e32 v142, v56, v66
	v_add_f32_e32 v143, 1.0, v107
	v_mul_f32_e32 v142, v91, v142
	v_fma_f32 v35, v143, v142, v123
	v_max_f32_e64 v30, |v26|, |v27|
	v_max3_f32 v30, |v24|, |v25|, v30
	v_max3_f32 v30, |v28|, |v67|, v30
	v_max3_f32 v30, |v29|, |v31|, v30
	v_max3_f32 v30, |v1|, |v59|, v30
	v_max3_f32 v30, |v3|, |v23|, v30
	v_max3_f32 v30, |v20|, |v21|, v30
	v_max3_f32 v0, |v2|, |v35|, v30
	s_nop 1
	v_mov_b32_dpp v22, v0 row_ror:8 row_mask:0xf bank_mask:0xf bound_ctrl:1
	v_max_f32_e32 v22, v22, v22
	v_max_f32_e32 v0, v0, v22
	s_nop 1
	v_mov_b32_dpp v22, v0 row_ror:4 row_mask:0xf bank_mask:0xf bound_ctrl:1
	v_max_f32_e32 v22, v22, v22
	v_max_f32_e32 v0, v0, v22
	s_nop 1
	v_mov_b32_dpp v22, v0 row_ror:2 row_mask:0xf bank_mask:0xf bound_ctrl:1
	v_max_f32_e32 v22, v22, v22
	v_max_f32_e32 v0, v0, v22
	s_nop 1
	v_mov_b32_dpp v22, v0 row_ror:1 row_mask:0xf bank_mask:0xf bound_ctrl:1
	v_max_f32_e32 v22, v22, v22
	v_max_f32_e32 v0, v0, v22
	s_nop 1
	v_mov_b32_e32 v22, v0
	s_nop 1
	v_permlane16_swap_b32_e32 v22, v0
	s_nop 1
	v_max_f32_e32 v0, v0, v22
	s_nop 1
	v_mov_b32_e32 v22, v0
	s_nop 1
	v_permlane32_swap_b32_e32 v22, v0
	s_nop 1
	v_max_f32_e32 v0, v0, v22
	v_div_scale_f32 v22, s[16:17], v0, v0, s20
	v_rcp_f32_e32 v30, v22
	v_cmp_lt_f32_e64 s[10:11], 0, v0
	v_fma_f32 v32, -v22, v30, 1.0
	v_fmac_f32_e32 v30, v32, v30
	v_div_scale_f32 v32, vcc, s20, v0, s20
	v_mul_f32_e32 v33, v32, v30
	v_fma_f32 v34, -v22, v33, v32
	v_fmac_f32_e32 v33, v34, v30
	v_fma_f32 v22, -v22, v33, v32
	v_div_fmas_f32 v22, v22, v30, v33
	v_div_fixup_f32 v22, v22, v0, s20
	v_cndmask_b32_e64 v22, 1.0, v22, s[10:11]
	v_mul_f32_e32 v24, v24, v22
	v_mul_f32_e32 v25, v25, v22
	v_mov_b32_e32 v30, 0
	v_cvt_pk_fp8_f32 v30, v24, v25
	v_mul_f32_e32 v24, v26, v22
	v_mul_f32_e32 v25, v27, v22
	v_mov_b32_e32 v26, 0
	v_cvt_pk_fp8_f32 v30, v24, v25 op_sel:[0,0,1]
	v_mul_f32_e32 v24, v28, v22
	v_mul_f32_e32 v25, v67, v22
	v_cvt_pk_fp8_f32 v26, v24, v25
	v_mul_f32_e32 v24, v29, v22
	v_mul_f32_e32 v25, v31, v22
	v_mul_f32_e32 v1, v1, v22
	v_cvt_pk_fp8_f32 v26, v24, v25 op_sel:[0,0,1]
	v_mul_f32_e32 v24, v59, v22
	v_mov_b32_e32 v25, 0
	v_cvt_pk_fp8_f32 v25, v1, v24
	v_mul_f32_e32 v1, v3, v22
	v_mul_f32_e32 v3, v23, v22
	global_store_dword v[46:47], v30, off
	v_cvt_pk_fp8_f32 v25, v1, v3 op_sel:[0,0,1]
	v_mul_f32_e32 v1, v20, v22
	v_mul_f32_e32 v3, v21, v22
	v_mov_b32_e32 v20, 0
	v_cvt_pk_fp8_f32 v20, v1, v3
	v_mul_f32_e32 v1, v2, v22
	v_mul_f32_e32 v2, v35, v22
	global_store_dword v[46:47], v26, off offset:256
	v_cvt_pk_fp8_f32 v20, v1, v2 op_sel:[0,0,1]
	global_store_dword v[46:47], v25, off offset:512
	global_store_dword v[46:47], v20, off offset:768
	s_and_saveexec_b64 s[16:17], s[6:7]
	s_cbranch_execz .LBB0_209
	v_mul_f32_e32 v0, 0x3b924925, v0
	v_cndmask_b32_e64 v0, 1.0, v0, s[10:11]
	global_store_dword v[44:45], v0, off
	s_branch .LBB0_209
